# first phase seam uses the same XCD-hierarchical barrier block as every other seam instead of the cooperative-groups grid sync
# speedup vs baseline: 1.0050x; 1.0050x over previous
; __device__ __forceinline__ unsigned xb_ld(unsigned* p)              { return __hip_atomic_load(p, __ATOMIC_RELAXED, __HIP_MEMORY_SCOPE_AGENT); }
; __device__ __forceinline__ unsigned xb_add(unsigned* p, unsigned v) { return __hip_atomic_fetch_add(p, v, __ATOMIC_RELAXED, __HIP_MEMORY_SCOPE_AGENT); }
; __device__ __forceinline__ void xcd_barrier_complete(unsigned* bar, unsigned x, unsigned& nloc, unsigned& nx) {
;     const unsigned G = gridDim.x * gridDim.y * gridDim.z;
;     unsigned sum, cnt, mine, sp = 0u;
;     for (;;) {
;         sum = 0u; cnt = 0u; mine = 0u;
; #pragma unroll
;         for (unsigned j = 0; j < 16; ++j) { const unsigned c = xb_ld(&bar[XB_XCNT(j)]); sum += c; cnt += (c > 0u) ? 1u : 0u; mine = (j == x) ? c : mine; }
; __device__ __forceinline__ void xcd_barrier(const XcdBarrier& b) {
;     asm volatile("s_waitcnt vmcnt(0)" ::: "memory");
;     __syncthreads();
;     if (threadIdx.x == 0) {
;         unsigned* bar = b.bar;
;         __builtin_amdgcn_s_waitcnt(0);
;         unsigned nloc = b.st[0], nx = b.st[1];
;         if (nloc == 0u) { xcd_barrier_complete(bar, b.x, nloc, nx); b.st[0] = nloc; b.st[1] = nx; }
;         const unsigned old = xb_add(&bar[XB_XSUB(b.x)], 1u);
.LBB0_62:
	s_or_b64 exec, exec, s[4:5]
	s_waitcnt vmcnt(0)
	s_waitcnt vmcnt(0) lgkmcnt(0)
	s_barrier
	s_and_saveexec_b64 s[4:5], s[34:35]
	s_cbranch_execz .LBB0_72
	s_add_i32 s6, 0, 0x20000
	v_mov_b32_e32 v0, s6
	s_waitcnt vmcnt(0) expcnt(0) lgkmcnt(0)
	ds_read_b32 v2, v0
	s_add_i32 s6, 0, 0x20004
	v_mov_b32_e32 v0, s6
	ds_read_b32 v0, v0
	s_waitcnt lgkmcnt(1)
	v_cmp_ne_u32_e32 vcc, 0, v2
	s_cbranch_vccnz .Lseam0_100
	s_add_u32 s6, s42, 0x2dd20200
	s_addc_u32 s7, s43, 0
	s_add_u32 s8, s42, 0x2dd20400
	s_addc_u32 s9, s43, 0
	s_add_u32 s10, s42, 0x2dd20500
	s_addc_u32 s11, s43, 0
	s_add_u32 s12, s42, 0x2dd20600
	s_addc_u32 s13, s43, 0
	s_add_u32 s14, s42, 0x2dd20700
	s_addc_u32 s15, s43, 0
	s_add_u32 s16, s42, 0x2dd20800
	s_addc_u32 s17, s43, 0
	s_add_u32 s18, s42, 0x2dd20900
	s_addc_u32 s19, s43, 0
	s_add_u32 s20, s42, 0x2dd20a00
	s_addc_u32 s21, s43, 0
	s_add_u32 s22, s42, 0x2dd20b00
	s_addc_u32 s23, s43, 0
	s_add_u32 s24, s42, 0x2dd20c00
	s_addc_u32 s25, s43, 0
	s_add_u32 s26, s42, 0x2dd20d00
	s_addc_u32 s27, s43, 0
	s_add_u32 s28, s42, 0x2dd20e00
	s_addc_u32 s29, s43, 0
	s_add_u32 s30, s42, 0x2dd20f00
	s_addc_u32 s31, s43, 0
	s_add_u32 s36, s42, 0x2dd21000
	s_addc_u32 s37, s43, 0
	s_add_u32 s38, s42, 0x2dd21100
	s_addc_u32 s39, s43, 0
	s_add_u32 s46, s42, 0x2dd21200
	s_addc_u32 s47, s43, 0
	s_mul_i32 s56, s41, s33
	s_add_u32 s48, s42, 0x2dd21300
	s_mul_i32 s56, s56, s40
	s_addc_u32 s49, s43, 0
	s_mov_b32 s57, 1
	v_mov_b32_e32 v16, 0
	s_branch .Lseam0_88

; #define PG8_LAS __attribute__((address_space(3)))
; template <class Epi, class Sched>
; __device__ __forceinline__ void gemm_phase(PG8_LAS unsigned char* lds, const Gemm g, const Sched& S, const Epi& E) {
;     int tix_ = threadIdx.x; asm volatile("" : "+v"(tix_));
;     const int tid = tix_, wid = __builtin_amdgcn_readfirstlane(tid >> 6), lane = tid & 63, wr = wid >> 2, wc = wid & 3, fr = lane & 15, fq = lane >> 4;
;     const int K = g.K, nt = K / BK;
;     unsigned voffA[2], voffB[2];
; #pragma unroll
;     for (int i = 0; i < 2; ++i) { int R, C; stage_rc(tid * 16 + i * 8192, R, C);
;         voffA[i] = (unsigned)(R * K + C) * 2u; voffB[i] = (unsigned)(tid * 16 + i * 8192); }
;     const size_t kstep = (size_t)(BK * 2);
;     const size_t hstep = (size_t)HALF * K * 2;
;     const size_t tstep = 2 * hstep;
;     const size_t kstepB = 32768, hstepB = 16384, tstepB = (size_t)nt * 32768;
;     const unsigned ldsw = (unsigned)wid * 1024u;
;     const int aoff = lds_byte(wr * 64 + fr, fq * 8), boff = lds_byte(wc * 32 + fr, fq * 8);
;     ...
;     Unit cur, nxt; int ui = 0;
;     if (!S.next(0, cur)) return;
;     f32x4 acc[2][2][4][2];
; #pragma unroll
;     for (int a = 0; a < 2; ++a)
; #pragma unroll
;         for (int b = 0; b < 2; ++b)
; #pragma unroll
;             for (int m = 0; m < 4; ++m)
; #pragma unroll
;                 for (int n = 0; n < 2; ++n) acc[a][b][m][n] = (f32x4){0.f, 0.f, 0.f, 0.f};
;     bf16x8 At[4][2], B0[2][2], B1[2][2];
;     const char* cA = (const char*)g.A + (size_t)cur.pm * tstep + (size_t)cur.br * g.strideA; const char* cB = (const char*)g.Bt + (size_t)cur.pn * tstepB + (size_t)cur.br * g.strideB;
;     S.a_ready(cur);
;     PG8_STAGE(PG8_SB(0, 0), cB, voffB); PG8_STAGE(PG8_SA(0, 0), cA, voffA); PG8_STAGE(PG8_SB(0, 1), cB + hstepB, voffB); PG8_STAGE(PG8_SA(0, 1), cA + hstep, voffA);
;     if (wr == 1) PG8_BAR;
;     PG8_WAIT_V(4); PG8_BAR;
;     PG8_STAGE(PG8_SB(1, 0), cB + kstepB, voffB); PG8_STAGE(PG8_SA(1, 0), cA + kstep, voffA); PG8_STAGE(PG8_SB(1, 1), cB + hstepB + kstepB, voffB);
;     PG8_WAIT_V(6); PG8_BAR;
; __device__ __forceinline__ void xcd_barrier(const XcdBarrier& b) {
;     ...
;             XB_SPIN(xb_ld(&bar[XB_XGEN(b.x)]) == gen, bar);
;             __builtin_amdgcn_fence(__ATOMIC_ACQUIRE, "agent");
;             asm volatile("s_waitcnt vmcnt(0)" ::: "memory");
;         }
;     }
;     __syncthreads();
.Lseam0_135:
	s_or_b64 exec, exec, s[10:11]
	s_waitcnt vmcnt(0)
.LBB0_72:
	s_or_b64 exec, exec, s[4:5]
	s_mov_b64 s[4:5], s[0:1]
	s_mov_b32 s28, s40
	s_mov_b32 s29, s2
	v_mov_b32_e32 v4, v228
	s_barrier
	s_cmpk_gt_i32 s29, 0xabf
	v_readfirstlane_b32 s30, v4
	s_cbranch_scc1 .LBB0_84
	s_load_dwordx2 s[6:7], s[4:5], 0xa8
	v_lshlrev_b32_e32 v128, 4, v4
	s_mul_hi_i32 s4, s29, 0x2fa0be83
	v_add_u32_e32 v130, 0x2000, v128
	v_ashrrev_i32_e32 v0, 31, v130
	s_waitcnt lgkmcnt(0)
	s_add_u32 s31, s6, 0xc700000
	s_addc_u32 s36, s7, 0
	s_lshr_b32 s8, s4, 31
	s_lshr_b32 s4, s4, 9
	s_add_i32 s4, s4, s8
	v_lshrrev_b32_e32 v0, 22, v0
	s_mulk_i32 s4, 0xac0
	v_add_u32_e32 v0, v130, v0
	s_sub_i32 s4, s29, s4
	v_ashrrev_i32_e32 v5, 10, v0
	s_sext_i32_i16 s8, s4
	v_mul_i32_i24_e32 v1, 0x400, v5
	s_bfe_u32 s8, s8, 0x3001c
	v_sub_u32_e32 v1, v130, v1
	s_add_i32 s8, s4, s8
	v_lshrrev_b32_e32 v2, 4, v1
	s_sext_i32_i16 s9, s8
	s_and_b32 s8, s8, 0xfff8
	s_ashr_i32 s10, s30, 6
	v_bitop3_b32 v1, v2, v1, 32 bitop3:0x6c
	s_sub_i32 s4, s4, s8
	s_ashr_i32 s5, s30, 8
	s_ashr_i32 s37, s29, 31
	s_lshl_b32 s38, s10, 10
	v_ashrrev_i32_e32 v2, 31, v1
	s_ashr_i32 s9, s9, 3
	s_sext_i32_i16 s8, s4
	v_lshrrev_b32_e32 v2, 26, v2
	s_cmp_lt_i32 s8, 0
	s_movk_i32 s39, 0x159
	v_add_u32_e32 v2, v1, v2
	s_cselect_b32 s8, s39, 0x158
	s_waitcnt vmcnt(10)
	v_ashrrev_i32_e32 v6, 6, v2
	v_and_b32_e32 v2, 0xc0, v2
	s_mul_i32 s4, s8, s4
	v_sub_u32_e32 v1, v1, v2
	v_mov_b32_e32 v2, 1
	s_add_i32 s4, s4, s9
	v_ashrrev_i16_sdwa v1, v2, sext(v1) dst_sel:DWORD dst_unused:UNUSED_PAD src0_sel:DWORD src1_sel:BYTE_0
	s_sext_i32_i16 s8, s4
	v_lshlrev_b32_e32 v0, 5, v5
	v_bfe_i32 v7, v1, 0, 16
	v_lshlrev_b32_e32 v1, 3, v5
	s_mulk_i32 s8, 0x2fa1
	v_and_b32_e32 v0, 32, v0
	v_and_b32_e32 v1, 0xffff0, v1
	s_lshr_b32 s9, s8, 31
	s_ashr_i32 s8, s8, 22
	v_add_u32_e32 v0, v0, v7
	v_add_lshl_u32 v1, v6, v1, 12
	s_add_i32 s8, s8, s9
	v_lshl_add_u32 v132, v0, 1, v1
	v_bfe_i32 v1, v4, 27, 1
	s_lshl_b32 s9, s8, 3
	s_mulk_i32 s8, 0x158
	v_lshrrev_b32_e32 v1, 22, v1
	s_sub_i32 s8, s4, s8
	v_add_u32_e32 v1, v128, v1
	s_sext_i32_i16 s4, s8
	v_and_b32_e32 v1, 0xfffffc00, v1
	s_bfe_u32 s4, s4, 0x3001c
	v_sub_u32_e32 v1, v128, v1
	s_add_i32 s11, s8, s4
	v_lshrrev_b32_e32 v3, 4, v1
	s_sext_i32_i16 s4, s11
	s_and_b32 s11, s11, 0xfff8
	v_bitop3_b32 v1, v3, v1, 32 bitop3:0x6c
	s_sub_i32 s8, s8, s11
	v_ashrrev_i32_e32 v3, 31, v1
	s_sext_i32_i16 s8, s8
	v_lshrrev_b32_e32 v3, 26, v3
	s_lshr_b32 s4, s4, 3
	s_add_i32 s20, s9, s8
	v_ashrrev_i32_e32 v0, 31, v4
	v_add_u32_e32 v3, v1, v3
	s_ashr_i32 s21, s20, 31
	s_bfe_i64 s[12:13], s[4:5], 0x100000
	v_lshrrev_b32_e32 v0, 26, v0
	v_ashrrev_i32_e32 v9, 6, v3
	v_and_b32_e32 v3, 0xc0, v3
	s_lshl_b64 s[8:9], s[20:21], 20
	s_lshl_b64 s[12:13], s[12:13], 20
	v_add_u32_e32 v0, v4, v0
	v_sub_u32_e32 v1, v1, v3
	s_add_u32 s22, s6, s12
	v_ashrrev_i32_e32 v8, 6, v0
	v_ashrrev_i16_sdwa v1, v2, sext(v1) dst_sel:DWORD dst_unused:UNUSED_PAD src0_sel:DWORD src1_sel:BYTE_0
	s_addc_u32 s23, s7, s13
	s_add_i32 s21, s38, 0
	v_lshlrev_b32_e32 v0, 5, v8
	s_waitcnt vmcnt(9)
	v_bfe_i32 v10, v1, 0, 16
	v_lshlrev_b32_e32 v1, 3, v8
	s_add_i32 m0, s21, 0x10000
	v_and_b32_e32 v0, 32, v0
	v_and_b32_e32 v1, 0xffff0, v1
	global_load_lds_dwordx4 v128, s[22:23]
	s_add_i32 m0, s21, 0x12000
	v_add_u32_e32 v0, v0, v10
	v_add_lshl_u32 v1, v9, v1, 12
	s_add_u32 s24, s31, s8
	v_lshl_add_u32 v134, v0, 1, v1
	global_load_lds_dwordx4 v130, s[22:23]
	s_addc_u32 s25, s36, s9
	s_mov_b32 m0, s21
	s_add_i32 s46, s21, 0x2000
	global_load_lds_dwordx4 v134, s[24:25]
	s_mov_b32 m0, s46
	s_add_u32 s8, s22, 0x4000
	global_load_lds_dwordx4 v132, s[24:25]
	s_addc_u32 s9, s23, 0
	s_add_i32 m0, s21, 0x14000
	v_mov_b32_e32 v129, 0
	global_load_lds_dwordx4 v128, s[8:9]
	s_add_i32 m0, s21, 0x16000
	v_mov_b32_e32 v135, v129
	global_load_lds_dwordx4 v130, s[8:9]
	s_add_u32 s8, s24, 0x80000
	s_addc_u32 s9, s25, 0
	s_add_i32 s47, s21, 0x4000
	s_mov_b32 m0, s47
	s_add_i32 s48, s21, 0x6000
	global_load_lds_dwordx4 v134, s[8:9]
	s_mov_b32 m0, s48
	v_mov_b32_e32 v133, v129
	global_load_lds_dwordx4 v132, s[8:9]
	s_mov_b32 s49, 0
	v_mov_b32_e32 v131, v129
	v_lshl_add_u64 v[2:3], s[24:25], 0, v[134:135]
	s_cmp_lg_u32 s5, 1
	v_lshl_add_u64 v[0:1], s[24:25], 0, v[132:133]
	s_cbranch_scc1 .LBB0_75
